# NSA top-k radix select: early exit once exactly 13 candidates remain >= the accepted prefix (identical selected set), on v_m23
# speedup vs baseline: 1.0055x; 1.0055x over previous
.LBB0_273:
	s_or_b64 exec, exec, s[12:13]
	v_cmp_gt_i32_e32 vcc, 0, v4
	s_bcnt1_i32_b64 s12, vcc
	v_cmp_gt_i32_e32 vcc, 0, v3
	s_bcnt1_i32_b64 s13, vcc
	s_add_i32 s13, s13, s12
	s_cmp_gt_u32 s13, 12
	s_cselect_b32 s12, 0x80000000, 0
	s_or_b32 s13, s12, 2.0
	v_cmp_le_u32_e32 vcc, s13, v4
	s_bcnt1_i32_b64 s14, vcc
	v_cmp_le_u32_e32 vcc, s13, v3
	s_bcnt1_i32_b64 s15, vcc
	s_add_i32 s15, s15, s14
	s_cmp_gt_u32 s15, 12
	s_cselect_b32 s12, s13, s12
	s_cmp_eq_u32 s15, 13
	s_cbranch_scc1 .Lmy_tk_0
	s_or_b32 s13, s12, 0x20000000
	v_cmp_le_u32_e32 vcc, s13, v4
	s_bcnt1_i32_b64 s14, vcc
	v_cmp_le_u32_e32 vcc, s13, v3
	s_bcnt1_i32_b64 s15, vcc
	s_add_i32 s15, s15, s14
	s_cmp_gt_u32 s15, 12
	s_cselect_b32 s12, s13, s12
	s_cmp_eq_u32 s15, 13
	s_cbranch_scc1 .Lmy_tk_0
	s_or_b32 s13, s12, 0x10000000
	v_cmp_le_u32_e32 vcc, s13, v4
	s_bcnt1_i32_b64 s14, vcc
	v_cmp_le_u32_e32 vcc, s13, v3
	s_bcnt1_i32_b64 s15, vcc
	s_add_i32 s15, s15, s14
	s_cmp_gt_u32 s15, 12
	s_cselect_b32 s12, s13, s12
	s_cmp_eq_u32 s15, 13
	s_cbranch_scc1 .Lmy_tk_0
	s_or_b32 s13, s12, 0x8000000
	v_cmp_le_u32_e32 vcc, s13, v4
	s_bcnt1_i32_b64 s14, vcc
	v_cmp_le_u32_e32 vcc, s13, v3
	s_bcnt1_i32_b64 s15, vcc
	s_add_i32 s15, s15, s14
	s_cmp_gt_u32 s15, 12
	s_cselect_b32 s12, s13, s12
	s_cmp_eq_u32 s15, 13
	s_cbranch_scc1 .Lmy_tk_0
	s_or_b32 s13, s12, 0x4000000
	v_cmp_le_u32_e32 vcc, s13, v4
	s_bcnt1_i32_b64 s14, vcc
	v_cmp_le_u32_e32 vcc, s13, v3
	s_bcnt1_i32_b64 s15, vcc
	s_add_i32 s15, s15, s14
	s_cmp_gt_u32 s15, 12
	s_cselect_b32 s12, s13, s12
	s_cmp_eq_u32 s15, 13
	s_cbranch_scc1 .Lmy_tk_0
	s_or_b32 s13, s12, 0x2000000
	v_cmp_le_u32_e32 vcc, s13, v4
	s_bcnt1_i32_b64 s14, vcc
	v_cmp_le_u32_e32 vcc, s13, v3
	s_bcnt1_i32_b64 s15, vcc
	s_add_i32 s15, s15, s14
	s_cmp_gt_u32 s15, 12
	s_cselect_b32 s12, s13, s12
	s_cmp_eq_u32 s15, 13
	s_cbranch_scc1 .Lmy_tk_0
	s_or_b32 s13, s12, 0x1000000
	v_cmp_le_u32_e32 vcc, s13, v4
	s_bcnt1_i32_b64 s14, vcc
	v_cmp_le_u32_e32 vcc, s13, v3
	s_bcnt1_i32_b64 s15, vcc
	s_add_i32 s15, s15, s14
	s_cmp_gt_u32 s15, 12
	s_cselect_b32 s12, s13, s12
	s_cmp_eq_u32 s15, 13
	s_cbranch_scc1 .Lmy_tk_0
	s_or_b32 s13, s12, 0x800000
	v_cmp_le_u32_e32 vcc, s13, v4
	s_bcnt1_i32_b64 s14, vcc
	v_cmp_le_u32_e32 vcc, s13, v3
	s_bcnt1_i32_b64 s15, vcc
	s_add_i32 s15, s15, s14
	s_cmp_gt_u32 s15, 12
	s_cselect_b32 s12, s13, s12
	s_cmp_eq_u32 s15, 13
	s_cbranch_scc1 .Lmy_tk_0
	s_or_b32 s13, s12, 0x400000
	v_cmp_le_u32_e32 vcc, s13, v4
	s_bcnt1_i32_b64 s14, vcc
	v_cmp_le_u32_e32 vcc, s13, v3
	s_bcnt1_i32_b64 s15, vcc
	s_add_i32 s15, s15, s14
	s_cmp_gt_u32 s15, 12
	s_cselect_b32 s12, s13, s12
	s_cmp_eq_u32 s15, 13
	s_cbranch_scc1 .Lmy_tk_0
	s_or_b32 s13, s12, 0x200000
	v_cmp_le_u32_e32 vcc, s13, v4
	s_bcnt1_i32_b64 s14, vcc
	v_cmp_le_u32_e32 vcc, s13, v3
	s_bcnt1_i32_b64 s15, vcc
	s_add_i32 s15, s15, s14
	s_cmp_gt_u32 s15, 12
	s_cselect_b32 s12, s13, s12
	s_cmp_eq_u32 s15, 13
	s_cbranch_scc1 .Lmy_tk_0
	s_or_b32 s13, s12, 0x100000
	v_cmp_le_u32_e32 vcc, s13, v4
	s_bcnt1_i32_b64 s14, vcc
	v_cmp_le_u32_e32 vcc, s13, v3
	s_bcnt1_i32_b64 s15, vcc
	s_add_i32 s15, s15, s14
	s_cmp_gt_u32 s15, 12
	s_cselect_b32 s12, s13, s12
	s_cmp_eq_u32 s15, 13
	s_cbranch_scc1 .Lmy_tk_0
	s_or_b32 s13, s12, 0x80000
	v_cmp_le_u32_e32 vcc, s13, v4
	s_bcnt1_i32_b64 s14, vcc
	v_cmp_le_u32_e32 vcc, s13, v3
	s_bcnt1_i32_b64 s15, vcc
	s_add_i32 s15, s15, s14
	s_cmp_gt_u32 s15, 12
	s_cselect_b32 s12, s13, s12
	s_cmp_eq_u32 s15, 13
	s_cbranch_scc1 .Lmy_tk_0
	s_or_b32 s13, s12, 0x40000
	v_cmp_le_u32_e32 vcc, s13, v4
	s_bcnt1_i32_b64 s14, vcc
	v_cmp_le_u32_e32 vcc, s13, v3
	s_bcnt1_i32_b64 s15, vcc
	s_add_i32 s15, s15, s14
	s_cmp_gt_u32 s15, 12
	s_cselect_b32 s12, s13, s12
	s_cmp_eq_u32 s15, 13
	s_cbranch_scc1 .Lmy_tk_0
	s_or_b32 s13, s12, 0x20000
	v_cmp_le_u32_e32 vcc, s13, v4
	s_bcnt1_i32_b64 s14, vcc
	v_cmp_le_u32_e32 vcc, s13, v3
	s_bcnt1_i32_b64 s15, vcc
	s_add_i32 s15, s15, s14
	s_cmp_gt_u32 s15, 12
	s_cselect_b32 s12, s13, s12
	s_cmp_eq_u32 s15, 13
	s_cbranch_scc1 .Lmy_tk_0
	s_or_b32 s13, s12, 0x10000
	v_cmp_le_u32_e32 vcc, s13, v4
	s_bcnt1_i32_b64 s14, vcc
	v_cmp_le_u32_e32 vcc, s13, v3
	s_bcnt1_i32_b64 s15, vcc
	s_add_i32 s15, s15, s14
	s_cmp_gt_u32 s15, 12
	s_cselect_b32 s12, s13, s12
	s_cmp_eq_u32 s15, 13
	s_cbranch_scc1 .Lmy_tk_0
	s_or_b32 s13, s12, 0x8000
	v_cmp_le_u32_e32 vcc, s13, v4
	s_bcnt1_i32_b64 s14, vcc
	v_cmp_le_u32_e32 vcc, s13, v3
	s_bcnt1_i32_b64 s15, vcc
	s_add_i32 s15, s15, s14
	s_cmp_gt_u32 s15, 12
	s_cselect_b32 s12, s13, s12
	s_cmp_eq_u32 s15, 13
	s_cbranch_scc1 .Lmy_tk_0
	s_or_b32 s13, s12, 0x4000
	v_cmp_le_u32_e32 vcc, s13, v4
	s_bcnt1_i32_b64 s14, vcc
	v_cmp_le_u32_e32 vcc, s13, v3
	s_bcnt1_i32_b64 s15, vcc
	s_add_i32 s15, s15, s14
	s_cmp_gt_u32 s15, 12
	s_cselect_b32 s12, s13, s12
	s_cmp_eq_u32 s15, 13
	s_cbranch_scc1 .Lmy_tk_0
	s_or_b32 s13, s12, 0x2000
	v_cmp_le_u32_e32 vcc, s13, v4
	s_bcnt1_i32_b64 s14, vcc
	v_cmp_le_u32_e32 vcc, s13, v3
	s_bcnt1_i32_b64 s15, vcc
	s_add_i32 s15, s15, s14
	s_cmp_gt_u32 s15, 12
	s_cselect_b32 s12, s13, s12
	s_cmp_eq_u32 s15, 13
	s_cbranch_scc1 .Lmy_tk_0
	s_or_b32 s13, s12, 0x1000
	v_cmp_le_u32_e32 vcc, s13, v4
	s_bcnt1_i32_b64 s14, vcc
	v_cmp_le_u32_e32 vcc, s13, v3
	s_bcnt1_i32_b64 s15, vcc
	s_add_i32 s15, s15, s14
	s_cmp_gt_u32 s15, 12
	s_cselect_b32 s12, s13, s12
	s_cmp_eq_u32 s15, 13
	s_cbranch_scc1 .Lmy_tk_0
	s_or_b32 s13, s12, 0x800
	v_cmp_le_u32_e32 vcc, s13, v4
	s_bcnt1_i32_b64 s14, vcc
	v_cmp_le_u32_e32 vcc, s13, v3
	s_bcnt1_i32_b64 s15, vcc
	s_add_i32 s15, s15, s14
	s_cmp_gt_u32 s15, 12
	s_cselect_b32 s12, s13, s12
	s_cmp_eq_u32 s15, 13
	s_cbranch_scc1 .Lmy_tk_0
	s_or_b32 s13, s12, 0x400
	v_cmp_le_u32_e32 vcc, s13, v4
	s_bcnt1_i32_b64 s14, vcc
	v_cmp_le_u32_e32 vcc, s13, v3
	s_bcnt1_i32_b64 s15, vcc
	s_add_i32 s15, s15, s14
	s_cmp_gt_u32 s15, 12
	s_cselect_b32 s12, s13, s12
	s_cmp_eq_u32 s15, 13
	s_cbranch_scc1 .Lmy_tk_0
	s_or_b32 s13, s12, 0x200
	v_cmp_le_u32_e32 vcc, s13, v4
	s_bcnt1_i32_b64 s14, vcc
	v_cmp_le_u32_e32 vcc, s13, v3
	s_bcnt1_i32_b64 s15, vcc
	s_add_i32 s15, s15, s14
	s_cmp_gt_u32 s15, 12
	s_cselect_b32 s12, s13, s12
	s_cmp_eq_u32 s15, 13
	s_cbranch_scc1 .Lmy_tk_0
	s_or_b32 s13, s12, 0x100
	v_cmp_le_u32_e32 vcc, s13, v4
	s_bcnt1_i32_b64 s14, vcc
	v_cmp_le_u32_e32 vcc, s13, v3
	s_bcnt1_i32_b64 s15, vcc
	s_add_i32 s15, s15, s14
	s_cmp_gt_u32 s15, 12
	s_cselect_b32 s12, s13, s12
	s_cmp_eq_u32 s15, 13
	s_cbranch_scc1 .Lmy_tk_0
	s_or_b32 s13, s12, 0x80
	v_cmp_le_u32_e32 vcc, s13, v4
	s_bcnt1_i32_b64 s14, vcc
	v_cmp_le_u32_e32 vcc, s13, v3
	s_bcnt1_i32_b64 s15, vcc
	s_add_i32 s15, s15, s14
	s_cmp_gt_u32 s15, 12
	s_cselect_b32 s12, s13, s12
	s_cmp_eq_u32 s15, 13
	s_cbranch_scc1 .Lmy_tk_0
	s_or_b32 s13, s12, 64
	v_cmp_le_u32_e32 vcc, s13, v4
	s_bcnt1_i32_b64 s14, vcc
	v_cmp_le_u32_e32 vcc, s13, v3
	s_bcnt1_i32_b64 s15, vcc
	s_add_i32 s15, s15, s14
	s_cmp_gt_u32 s15, 12
	s_cselect_b32 s12, s13, s12
	s_cmp_eq_u32 s15, 13
	s_cbranch_scc1 .Lmy_tk_0
	s_or_b32 s13, s12, 32
	v_cmp_le_u32_e32 vcc, s13, v4
	s_bcnt1_i32_b64 s14, vcc
	v_cmp_le_u32_e32 vcc, s13, v3
	s_bcnt1_i32_b64 s15, vcc
	s_add_i32 s15, s15, s14
	s_cmp_gt_u32 s15, 12
	s_cselect_b32 s12, s13, s12
	s_cmp_eq_u32 s15, 13
	s_cbranch_scc1 .Lmy_tk_0
	s_or_b32 s13, s12, 16
	v_cmp_le_u32_e32 vcc, s13, v4
	s_bcnt1_i32_b64 s14, vcc
	v_cmp_le_u32_e32 vcc, s13, v3
	s_bcnt1_i32_b64 s15, vcc
	s_add_i32 s15, s15, s14
	s_cmp_gt_u32 s15, 12
	s_cselect_b32 s12, s13, s12
	s_cmp_eq_u32 s15, 13
	s_cbranch_scc1 .Lmy_tk_0
	s_or_b32 s13, s12, 8
	v_cmp_le_u32_e32 vcc, s13, v4
	s_bcnt1_i32_b64 s14, vcc
	v_cmp_le_u32_e32 vcc, s13, v3
	s_bcnt1_i32_b64 s15, vcc
	s_add_i32 s15, s15, s14
	s_cmp_gt_u32 s15, 12
	s_cselect_b32 s12, s13, s12
	s_cmp_eq_u32 s15, 13
	s_cbranch_scc1 .Lmy_tk_0
	s_or_b32 s13, s12, 4
	v_cmp_le_u32_e32 vcc, s13, v4
	s_bcnt1_i32_b64 s14, vcc
	v_cmp_le_u32_e32 vcc, s13, v3
	s_bcnt1_i32_b64 s15, vcc
	s_add_i32 s15, s15, s14
	s_cmp_gt_u32 s15, 12
	s_cselect_b32 s12, s13, s12
	s_cmp_eq_u32 s15, 13
	s_cbranch_scc1 .Lmy_tk_0
	s_or_b32 s13, s12, 2
	v_cmp_le_u32_e32 vcc, s13, v4
	s_bcnt1_i32_b64 s14, vcc
	v_cmp_le_u32_e32 vcc, s13, v3
	s_bcnt1_i32_b64 s15, vcc
	s_add_i32 s15, s15, s14
	s_cmp_gt_u32 s15, 12
	s_cselect_b32 s12, s13, s12
	s_cmp_eq_u32 s15, 13
	s_cbranch_scc1 .Lmy_tk_0
	s_or_b32 s13, s12, 1
	v_cmp_le_u32_e32 vcc, s13, v4
	s_bcnt1_i32_b64 s14, vcc
	v_cmp_le_u32_e32 vcc, s13, v3
	s_bcnt1_i32_b64 s15, vcc
	s_add_i32 s15, s15, s14
	s_cmp_gt_u32 s15, 12
	s_cselect_b32 s12, s13, s12
.Lmy_tk_0:
	v_cmp_lt_u32_e32 vcc, s12, v4
	v_cmp_lt_u32_e64 s[46:47], s12, v3
	v_cmp_eq_u32_e64 s[52:53], s12, v4
	v_cndmask_b32_e64 v5, 0, 1, vcc
	v_cmp_ne_u32_e64 s[44:45], 0, v5
	v_cndmask_b32_e64 v5, 0, 1, s[46:47]
	v_cmp_ne_u32_e64 s[48:49], 0, v5
	v_cmp_eq_u32_e64 s[54:55], s12, v3
	v_and_b32_e32 v4, s52, v2
	s_bcnt1_i32_b64 s12, s[44:45]
	s_bcnt1_i32_b64 s13, s[48:49]
	v_and_b32_e32 v3, s53, v0
	v_bcnt_u32_b32 v4, v4, 0
	v_and_b32_e32 v5, s54, v2
	s_add_i32 s12, s12, s13
	v_bcnt_u32_b32 v3, v3, v4
	v_and_b32_e32 v4, s55, v0
	v_bcnt_u32_b32 v5, v5, 0
	s_sub_i32 s14, 13, s12
	s_bcnt1_i32_b64 s12, s[52:53]
	v_bcnt_u32_b32 v4, v4, v5
	v_add_u32_e32 v4, s12, v4
	v_cmp_gt_i32_e64 s[44:45], s14, v3
	s_and_b64 s[12:13], s[52:53], s[44:45]
	v_cmp_gt_i32_e64 s[44:45], s14, v4
	s_and_b64 s[14:15], s[54:55], s[44:45]
	s_or_b64 s[44:45], s[82:83], vcc
	s_or_b64 s[12:13], s[44:45], s[12:13]
	s_or_b64 s[44:45], s[90:91], s[46:47]
	s_or_b64 s[14:15], s[44:45], s[14:15]

.LBB0_288:
	s_or_b64 exec, exec, s[0:1]
	v_cmp_gt_i32_e32 vcc, 0, v5
	s_bcnt1_i32_b64 s0, vcc
	v_cmp_gt_i32_e32 vcc, 0, v4
	s_bcnt1_i32_b64 s1, vcc
	s_add_i32 s1, s1, s0
	s_cmp_gt_u32 s1, 12
	s_cselect_b32 s0, 0x80000000, 0
	s_or_b32 s1, s0, 2.0
	v_cmp_le_u32_e32 vcc, s1, v5
	s_bcnt1_i32_b64 s12, vcc
	v_cmp_le_u32_e32 vcc, s1, v4
	s_bcnt1_i32_b64 s13, vcc
	s_add_i32 s13, s13, s12
	s_cmp_gt_u32 s13, 12
	s_cselect_b32 s0, s1, s0
	s_cmp_eq_u32 s13, 13
	s_cbranch_scc1 .Lmy_tk_1
	s_or_b32 s1, s0, 0x20000000
	v_cmp_le_u32_e32 vcc, s1, v5
	s_bcnt1_i32_b64 s12, vcc
	v_cmp_le_u32_e32 vcc, s1, v4
	s_bcnt1_i32_b64 s13, vcc
	s_add_i32 s13, s13, s12
	s_cmp_gt_u32 s13, 12
	s_cselect_b32 s0, s1, s0
	s_cmp_eq_u32 s13, 13
	s_cbranch_scc1 .Lmy_tk_1
	s_or_b32 s1, s0, 0x10000000
	v_cmp_le_u32_e32 vcc, s1, v5
	s_bcnt1_i32_b64 s12, vcc
	v_cmp_le_u32_e32 vcc, s1, v4
	s_bcnt1_i32_b64 s13, vcc
	s_add_i32 s13, s13, s12
	s_cmp_gt_u32 s13, 12
	s_cselect_b32 s0, s1, s0
	s_cmp_eq_u32 s13, 13
	s_cbranch_scc1 .Lmy_tk_1
	s_or_b32 s1, s0, 0x8000000
	v_cmp_le_u32_e32 vcc, s1, v5
	s_bcnt1_i32_b64 s12, vcc
	v_cmp_le_u32_e32 vcc, s1, v4
	s_bcnt1_i32_b64 s13, vcc
	s_add_i32 s13, s13, s12
	s_cmp_gt_u32 s13, 12
	s_cselect_b32 s0, s1, s0
	s_cmp_eq_u32 s13, 13
	s_cbranch_scc1 .Lmy_tk_1
	s_or_b32 s1, s0, 0x4000000
	v_cmp_le_u32_e32 vcc, s1, v5
	s_bcnt1_i32_b64 s12, vcc
	v_cmp_le_u32_e32 vcc, s1, v4
	s_bcnt1_i32_b64 s13, vcc
	s_add_i32 s13, s13, s12
	s_cmp_gt_u32 s13, 12
	s_cselect_b32 s0, s1, s0
	s_cmp_eq_u32 s13, 13
	s_cbranch_scc1 .Lmy_tk_1
	s_or_b32 s1, s0, 0x2000000
	v_cmp_le_u32_e32 vcc, s1, v5
	s_bcnt1_i32_b64 s12, vcc
	v_cmp_le_u32_e32 vcc, s1, v4
	s_bcnt1_i32_b64 s13, vcc
	s_add_i32 s13, s13, s12
	s_cmp_gt_u32 s13, 12
	s_cselect_b32 s0, s1, s0
	s_cmp_eq_u32 s13, 13
	s_cbranch_scc1 .Lmy_tk_1
	s_or_b32 s1, s0, 0x1000000
	v_cmp_le_u32_e32 vcc, s1, v5
	s_bcnt1_i32_b64 s12, vcc
	v_cmp_le_u32_e32 vcc, s1, v4
	s_bcnt1_i32_b64 s13, vcc
	s_add_i32 s13, s13, s12
	s_cmp_gt_u32 s13, 12
	s_cselect_b32 s0, s1, s0
	s_cmp_eq_u32 s13, 13
	s_cbranch_scc1 .Lmy_tk_1
	s_or_b32 s1, s0, 0x800000
	v_cmp_le_u32_e32 vcc, s1, v5
	s_bcnt1_i32_b64 s12, vcc
	v_cmp_le_u32_e32 vcc, s1, v4
	s_bcnt1_i32_b64 s13, vcc
	s_add_i32 s13, s13, s12
	s_cmp_gt_u32 s13, 12
	s_cselect_b32 s0, s1, s0
	s_cmp_eq_u32 s13, 13
	s_cbranch_scc1 .Lmy_tk_1
	s_or_b32 s1, s0, 0x400000
	v_cmp_le_u32_e32 vcc, s1, v5
	s_bcnt1_i32_b64 s12, vcc
	v_cmp_le_u32_e32 vcc, s1, v4
	s_bcnt1_i32_b64 s13, vcc
	s_add_i32 s13, s13, s12
	s_cmp_gt_u32 s13, 12
	s_cselect_b32 s0, s1, s0
	s_cmp_eq_u32 s13, 13
	s_cbranch_scc1 .Lmy_tk_1
	s_or_b32 s1, s0, 0x200000
	v_cmp_le_u32_e32 vcc, s1, v5
	s_bcnt1_i32_b64 s12, vcc
	v_cmp_le_u32_e32 vcc, s1, v4
	s_bcnt1_i32_b64 s13, vcc
	s_add_i32 s13, s13, s12
	s_cmp_gt_u32 s13, 12
	s_cselect_b32 s0, s1, s0
	s_cmp_eq_u32 s13, 13
	s_cbranch_scc1 .Lmy_tk_1
	s_or_b32 s1, s0, 0x100000
	v_cmp_le_u32_e32 vcc, s1, v5
	s_bcnt1_i32_b64 s12, vcc
	v_cmp_le_u32_e32 vcc, s1, v4
	s_bcnt1_i32_b64 s13, vcc
	s_add_i32 s13, s13, s12
	s_cmp_gt_u32 s13, 12
	s_cselect_b32 s0, s1, s0
	s_cmp_eq_u32 s13, 13
	s_cbranch_scc1 .Lmy_tk_1
	s_or_b32 s1, s0, 0x80000
	v_cmp_le_u32_e32 vcc, s1, v5
	s_bcnt1_i32_b64 s12, vcc
	v_cmp_le_u32_e32 vcc, s1, v4
	s_bcnt1_i32_b64 s13, vcc
	s_add_i32 s13, s13, s12
	s_cmp_gt_u32 s13, 12
	s_cselect_b32 s0, s1, s0
	s_cmp_eq_u32 s13, 13
	s_cbranch_scc1 .Lmy_tk_1
	s_or_b32 s1, s0, 0x40000
	v_cmp_le_u32_e32 vcc, s1, v5
	s_bcnt1_i32_b64 s12, vcc
	v_cmp_le_u32_e32 vcc, s1, v4
	s_bcnt1_i32_b64 s13, vcc
	s_add_i32 s13, s13, s12
	s_cmp_gt_u32 s13, 12
	s_cselect_b32 s0, s1, s0
	s_cmp_eq_u32 s13, 13
	s_cbranch_scc1 .Lmy_tk_1
	s_or_b32 s1, s0, 0x20000
	v_cmp_le_u32_e32 vcc, s1, v5
	s_bcnt1_i32_b64 s12, vcc
	v_cmp_le_u32_e32 vcc, s1, v4
	s_bcnt1_i32_b64 s13, vcc
	s_add_i32 s13, s13, s12
	s_cmp_gt_u32 s13, 12
	s_cselect_b32 s0, s1, s0
	s_cmp_eq_u32 s13, 13
	s_cbranch_scc1 .Lmy_tk_1
	s_or_b32 s1, s0, 0x10000
	v_cmp_le_u32_e32 vcc, s1, v5
	s_bcnt1_i32_b64 s12, vcc
	v_cmp_le_u32_e32 vcc, s1, v4
	s_bcnt1_i32_b64 s13, vcc
	s_add_i32 s13, s13, s12
	s_cmp_gt_u32 s13, 12
	s_cselect_b32 s0, s1, s0
	s_cmp_eq_u32 s13, 13
	s_cbranch_scc1 .Lmy_tk_1
	s_or_b32 s1, s0, 0x8000
	v_cmp_le_u32_e32 vcc, s1, v5
	s_bcnt1_i32_b64 s12, vcc
	v_cmp_le_u32_e32 vcc, s1, v4
	s_bcnt1_i32_b64 s13, vcc
	s_add_i32 s13, s13, s12
	s_cmp_gt_u32 s13, 12
	s_cselect_b32 s0, s1, s0
	s_cmp_eq_u32 s13, 13
	s_cbranch_scc1 .Lmy_tk_1
	s_or_b32 s1, s0, 0x4000
	v_cmp_le_u32_e32 vcc, s1, v5
	s_bcnt1_i32_b64 s12, vcc
	v_cmp_le_u32_e32 vcc, s1, v4
	s_bcnt1_i32_b64 s13, vcc
	s_add_i32 s13, s13, s12
	s_cmp_gt_u32 s13, 12
	s_cselect_b32 s0, s1, s0
	s_cmp_eq_u32 s13, 13
	s_cbranch_scc1 .Lmy_tk_1
	s_or_b32 s1, s0, 0x2000
	v_cmp_le_u32_e32 vcc, s1, v5
	s_bcnt1_i32_b64 s12, vcc
	v_cmp_le_u32_e32 vcc, s1, v4
	s_bcnt1_i32_b64 s13, vcc
	s_add_i32 s13, s13, s12
	s_cmp_gt_u32 s13, 12
	s_cselect_b32 s0, s1, s0
	s_cmp_eq_u32 s13, 13
	s_cbranch_scc1 .Lmy_tk_1
	s_or_b32 s1, s0, 0x1000
	v_cmp_le_u32_e32 vcc, s1, v5
	s_bcnt1_i32_b64 s12, vcc
	v_cmp_le_u32_e32 vcc, s1, v4
	s_bcnt1_i32_b64 s13, vcc
	s_add_i32 s13, s13, s12
	s_cmp_gt_u32 s13, 12
	s_cselect_b32 s0, s1, s0
	s_cmp_eq_u32 s13, 13
	s_cbranch_scc1 .Lmy_tk_1
	s_or_b32 s1, s0, 0x800
	v_cmp_le_u32_e32 vcc, s1, v5
	s_bcnt1_i32_b64 s12, vcc
	v_cmp_le_u32_e32 vcc, s1, v4
	s_bcnt1_i32_b64 s13, vcc
	s_add_i32 s13, s13, s12
	s_cmp_gt_u32 s13, 12
	s_cselect_b32 s0, s1, s0
	s_cmp_eq_u32 s13, 13
	s_cbranch_scc1 .Lmy_tk_1
	s_or_b32 s1, s0, 0x400
	v_cmp_le_u32_e32 vcc, s1, v5
	s_bcnt1_i32_b64 s12, vcc
	v_cmp_le_u32_e32 vcc, s1, v4
	s_bcnt1_i32_b64 s13, vcc
	s_add_i32 s13, s13, s12
	s_cmp_gt_u32 s13, 12
	s_cselect_b32 s0, s1, s0
	s_cmp_eq_u32 s13, 13
	s_cbranch_scc1 .Lmy_tk_1
	s_or_b32 s1, s0, 0x200
	v_cmp_le_u32_e32 vcc, s1, v5
	s_bcnt1_i32_b64 s12, vcc
	v_cmp_le_u32_e32 vcc, s1, v4
	s_bcnt1_i32_b64 s13, vcc
	s_add_i32 s13, s13, s12
	s_cmp_gt_u32 s13, 12
	s_cselect_b32 s0, s1, s0
	s_cmp_eq_u32 s13, 13
	s_cbranch_scc1 .Lmy_tk_1
	s_or_b32 s1, s0, 0x100
	v_cmp_le_u32_e32 vcc, s1, v5
	s_bcnt1_i32_b64 s12, vcc
	v_cmp_le_u32_e32 vcc, s1, v4
	s_bcnt1_i32_b64 s13, vcc
	s_add_i32 s13, s13, s12
	s_cmp_gt_u32 s13, 12
	s_cselect_b32 s0, s1, s0
	s_cmp_eq_u32 s13, 13
	s_cbranch_scc1 .Lmy_tk_1
	s_or_b32 s1, s0, 0x80
	v_cmp_le_u32_e32 vcc, s1, v5
	s_bcnt1_i32_b64 s12, vcc
	v_cmp_le_u32_e32 vcc, s1, v4
	s_bcnt1_i32_b64 s13, vcc
	s_add_i32 s13, s13, s12
	s_cmp_gt_u32 s13, 12
	s_cselect_b32 s0, s1, s0
	s_cmp_eq_u32 s13, 13
	s_cbranch_scc1 .Lmy_tk_1
	s_or_b32 s1, s0, 64
	v_cmp_le_u32_e32 vcc, s1, v5
	s_bcnt1_i32_b64 s12, vcc
	v_cmp_le_u32_e32 vcc, s1, v4
	s_bcnt1_i32_b64 s13, vcc
	s_add_i32 s13, s13, s12
	s_cmp_gt_u32 s13, 12
	s_cselect_b32 s0, s1, s0
	s_cmp_eq_u32 s13, 13
	s_cbranch_scc1 .Lmy_tk_1
	s_or_b32 s1, s0, 32
	v_cmp_le_u32_e32 vcc, s1, v5
	s_bcnt1_i32_b64 s12, vcc
	v_cmp_le_u32_e32 vcc, s1, v4
	s_bcnt1_i32_b64 s13, vcc
	s_add_i32 s13, s13, s12
	s_cmp_gt_u32 s13, 12
	s_cselect_b32 s0, s1, s0
	s_cmp_eq_u32 s13, 13
	s_cbranch_scc1 .Lmy_tk_1
	s_or_b32 s1, s0, 16
	v_cmp_le_u32_e32 vcc, s1, v5
	s_bcnt1_i32_b64 s12, vcc
	v_cmp_le_u32_e32 vcc, s1, v4
	s_bcnt1_i32_b64 s13, vcc
	s_add_i32 s13, s13, s12
	s_cmp_gt_u32 s13, 12
	s_cselect_b32 s0, s1, s0
	s_cmp_eq_u32 s13, 13
	s_cbranch_scc1 .Lmy_tk_1
	s_or_b32 s1, s0, 8
	v_cmp_le_u32_e32 vcc, s1, v5
	s_bcnt1_i32_b64 s12, vcc
	v_cmp_le_u32_e32 vcc, s1, v4
	s_bcnt1_i32_b64 s13, vcc
	s_add_i32 s13, s13, s12
	s_cmp_gt_u32 s13, 12
	s_cselect_b32 s0, s1, s0
	s_cmp_eq_u32 s13, 13
	s_cbranch_scc1 .Lmy_tk_1
	s_or_b32 s1, s0, 4
	v_cmp_le_u32_e32 vcc, s1, v5
	s_bcnt1_i32_b64 s12, vcc
	v_cmp_le_u32_e32 vcc, s1, v4
	s_bcnt1_i32_b64 s13, vcc
	s_add_i32 s13, s13, s12
	s_cmp_gt_u32 s13, 12
	s_cselect_b32 s0, s1, s0
	s_cmp_eq_u32 s13, 13
	s_cbranch_scc1 .Lmy_tk_1
	s_or_b32 s1, s0, 2
	v_cmp_le_u32_e32 vcc, s1, v5
	s_bcnt1_i32_b64 s12, vcc
	v_cmp_le_u32_e32 vcc, s1, v4
	s_bcnt1_i32_b64 s13, vcc
	s_add_i32 s13, s13, s12
	s_cmp_gt_u32 s13, 12
	s_cselect_b32 s0, s1, s0
	s_cmp_eq_u32 s13, 13
	s_cbranch_scc1 .Lmy_tk_1
	s_or_b32 s1, s0, 1
	v_cmp_le_u32_e32 vcc, s1, v5
	s_bcnt1_i32_b64 s12, vcc
	v_cmp_le_u32_e32 vcc, s1, v4
	s_bcnt1_i32_b64 s13, vcc
	s_add_i32 s13, s13, s12
	s_cmp_gt_u32 s13, 12
	s_cselect_b32 s0, s1, s0
.Lmy_tk_1:
	v_cmp_lt_u32_e32 vcc, s0, v5
	v_cmp_lt_u32_e64 s[48:49], s0, v4
	v_cmp_eq_u32_e64 s[54:55], s0, v5
	v_cndmask_b32_e64 v6, 0, 1, vcc
	v_cmp_ne_u32_e64 s[46:47], 0, v6
	v_cndmask_b32_e64 v6, 0, 1, s[48:49]
	v_cmp_ne_u32_e64 s[52:53], 0, v6
	v_cmp_eq_u32_e64 s[56:57], s0, v4
	v_and_b32_e32 v4, s54, v2
	s_bcnt1_i32_b64 s0, s[46:47]
	s_bcnt1_i32_b64 s1, s[52:53]
	v_and_b32_e32 v5, s55, v0
	v_bcnt_u32_b32 v4, v4, 0
	v_and_b32_e32 v6, s56, v2
	s_add_i32 s0, s0, s1
	v_bcnt_u32_b32 v4, v5, v4
	v_and_b32_e32 v5, s57, v0
	v_bcnt_u32_b32 v6, v6, 0
	s_sub_i32 s12, 13, s0
	s_bcnt1_i32_b64 s0, s[54:55]
	v_bcnt_u32_b32 v5, v5, v6
	v_add_u32_e32 v5, s0, v5
	v_cmp_gt_i32_e64 s[46:47], s12, v4
	s_and_b64 s[0:1], s[54:55], s[46:47]
	v_cmp_gt_i32_e64 s[46:47], s12, v5
	s_or_b64 s[14:15], s[82:83], vcc
	s_and_b64 s[12:13], s[56:57], s[46:47]
	s_or_b64 s[0:1], s[14:15], s[0:1]
	s_or_b64 s[14:15], s[90:91], s[48:49]
	s_or_b64 s[14:15], s[14:15], s[12:13]

.Lmy_tk_7:
	v_cmp_lt_u32_e32 vcc, s0, v5
	v_cmp_lt_u32_e64 s[44:45], s0, v4
	v_cmp_eq_u32_e64 s[48:49], s0, v5
	v_cndmask_b32_e64 v6, 0, 1, vcc
	v_cmp_ne_u32_e64 s[42:43], 0, v6
	v_cndmask_b32_e64 v6, 0, 1, s[44:45]
	v_cmp_ne_u32_e64 s[46:47], 0, v6
	v_cmp_eq_u32_e64 s[52:53], s0, v4
	s_bcnt1_i32_b64 s0, s[42:43]
	s_bcnt1_i32_b64 s1, s[46:47]
	v_and_b32_e32 v4, s48, v2
	v_and_b32_e32 v2, s52, v2
	s_add_i32 s0, s0, s1
	v_and_b32_e32 v5, s49, v0
	v_bcnt_u32_b32 v4, v4, 0
	v_and_b32_e32 v0, s53, v0
	v_bcnt_u32_b32 v2, v2, 0
	s_sub_i32 s12, 13, s0
	v_bcnt_u32_b32 v4, v5, v4
	s_bcnt1_i32_b64 s0, s[48:49]
	v_bcnt_u32_b32 v0, v0, v2
	v_add_u32_e32 v0, s0, v0
	v_cmp_gt_i32_e64 s[42:43], s12, v4
	s_and_b64 s[0:1], s[48:49], s[42:43]
	v_cmp_gt_i32_e64 s[42:43], s12, v0
	s_or_b64 s[14:15], s[82:83], vcc
	s_and_b64 s[12:13], s[52:53], s[42:43]
	s_or_b64 s[68:69], s[14:15], s[0:1]
	s_or_b64 s[0:1], s[90:91], s[44:45]
	s_or_b64 s[70:71], s[0:1], s[12:13]
